# GEMM units: first K-iteration peeled with SrcC=0 on each accumulator's first MFMA, the 128 per-unit accumulator-zeroing v_mov removed (in-proj / FFN-up / SC-in bodies)
# speedup vs baseline: 1.0168x; 1.0101x over previous
; #define PG8_STAGE(bufoff, gbase, voff) do { _Pragma("unroll") for (int _i = 0; _i < 2; ++_i) \
;         __builtin_amdgcn_global_load_lds((const unsigned*)((const char*)(gbase) + (voff)[_i]), (LAS unsigned*)(lds + (bufoff) + ldsw + _i * 8192), 16, 0, 0); } while (0)
; #define PG8_LDA(dst, b, h) do { _Pragma("unroll") for (int m = 0; m < 4; ++m) _Pragma("unroll") for (int k = 0; k < 2; ++k) dst[m][k] = *(const LAS bf16x8*)(lds + PG8_SA(b, h) + aoff + m * 2048 + k * 1024); } while (0)
; #define PG8_LDB(dst, b, h) do { _Pragma("unroll") for (int n = 0; n < 2; ++n) _Pragma("unroll") for (int k = 0; k < 2; ++k) dst[n][k] = *(const LAS bf16x8*)(lds + PG8_SB(b, h) + boff + n * 2048 + k * 1024); } while (0)
; #define PG8_MMA(ai, bj, At, Bt) do { __builtin_amdgcn_s_setprio(1); _Pragma("unroll") for (int m = 0; m < 4; ++m) _Pragma("unroll") for (int n = 0; n < 2; ++n) _Pragma("unroll") for (int k = 0; k < 2; ++k) \
;         acc[ai][bj][m][n] = __builtin_amdgcn_mfma_f32_16x16x32_bf16(Bt[n][k], At[m][k], acc[ai][bj][m][n], 0, 0, 0); __builtin_amdgcn_s_setprio(0); } while (0)
; #define PG8_WAIT_V(n) asm volatile("s_waitcnt vmcnt(" #n ")" ::: "memory")
; template <class Epi, bool ALIGN_EPI = true>
; __device__ __forceinline__ void gemm_phase(LAS unsigned char* lds, const Gemm g, const StaticOrder& S, const Epi& E) {
;     ...
;         for (int t = 0; t < nt; t += 2) {
;             const bool last = (t == nt - 2);
;             const char* a1 = cA + (size_t)(t + 1) * kstep;
;             const char* a2 = last ? nA : cA + (size_t)(t + 2) * kstep; const char* b2 = last ? nB : cB + (size_t)(t + 2) * kstep;
;             const char* a3 = a2 + kstep; const char* b3 = b2 + kstep;
;             PG8_LDB(B0, 0, 0); PG8_LDB(B1, 0, 1); PG8_SCHED; PG8_LDA(At, 0, 0); PG8_STAGE(PG8_SA(1, 1), a1 + hsA, voffA);
;             PG8_WAIT_V(8); PG8_WAIT_L(0); PG8_BAR; PG8_MMA(0, 0, At, B0); PG8_MMA(0, 1, At, B1); PG8_BAR; PG8_SCHED;
;             PG8_LDA(At, 0, 1); PG8_STAGE(PG8_SB(0, 0), b2, voffB); PG8_STAGE(PG8_SB(0, 1), b2 + hsB, voffB); PG8_STAGE(PG8_SA(0, 0), a2, voffA);
;     ...
; #pragma unroll
;         for (int a = 0; a < 2; ++a)
; #pragma unroll
;             for (int b = 0; b < 2; ++b)
; #pragma unroll
;                 for (int m = 0; m < 4; ++m)
; #pragma unroll
;                     for (int n = 0; n < 2; ++n) acc[a][b][m][n] = (f32x4){0.f, 0.f, 0.f, 0.f};
.LBB0_258:
	s_add_u32 s0, s8, 0x80
	s_addc_u32 s1, s9, 0
	s_add_u32 s8, s6, 0x100
	s_addc_u32 s9, s7, 0
	s_mov_b32 s6, 0
	v_readfirstlane_b32 s74, v0
	s_lshr_b32 s74, s74, 6
	s_cmp_ge_u32 s74, 4
	s_cbranch_scc0 .Lsp_skip_259
	s_setprio 1
.Lsp_skip_259:
	s_add_i32 s74, s6, 2
	s_add_u32 s75, s0, 0x80
	s_addc_u32 s7, s1, 0
	s_cmp_eq_u32 s72, s6
	s_cselect_b32 s7, s89, s7
	s_cselect_b32 s6, s88, s75
	s_cselect_b32 s81, s23, s9
	s_cselect_b32 s80, s22, s8
	s_add_i32 s75, 0, 0x14000
	v_add_u32_e32 v74, s91, v221
	v_add_u32_e32 v102, s75, v221
	ds_read_b128 v[58:61], v74
	ds_read_b128 v[66:69], v74 offset:1024
	ds_read_b128 v[70:73], v74 offset:2048
	ds_read_b128 v[74:77], v74 offset:3072
	ds_read_b128 v[90:93], v102
	ds_read_b128 v[94:97], v102 offset:1024
	ds_read_b128 v[98:101], v102 offset:2048
	ds_read_b128 v[102:105], v102 offset:3072
	v_lshl_add_u64 v[172:173], s[0:1], 0, v[180:181]
	s_add_i32 m0, s24, 0xc000
	ds_read_b128 v[184:187], v222
	ds_read_b128 v[188:191], v222 offset:1024
	ds_read_b128 v[192:195], v222 offset:2048
	ds_read_b128 v[196:199], v222 offset:3072
	ds_read_b128 v[200:203], v222 offset:4096
	ds_read_b128 v[224:227], v222 offset:5120
	ds_read_b128 v[228:231], v222 offset:6144
	ds_read_b128 v[232:235], v222 offset:7168
	global_load_lds_dwordx4 v[172:173], off
	v_lshl_add_u64 v[172:173], s[0:1], 0, v[182:183]
	s_add_i32 m0, s24, 0xe000
	s_nop 0
	global_load_lds_dwordx4 v[172:173], off
	s_waitcnt vmcnt(8)
	s_waitcnt lgkmcnt(0)
	s_barrier
	s_waitcnt lgkmcnt(0)
	v_mfma_f32_16x16x32_bf16 v[166:169], v[58:61], v[184:187], 0
	v_mfma_f32_16x16x32_bf16 v[162:165], v[70:73], v[184:187], 0
	v_mfma_f32_16x16x32_bf16 v[150:153], v[58:61], v[192:195], 0
	v_mfma_f32_16x16x32_bf16 v[146:149], v[70:73], v[192:195], 0
	v_mfma_f32_16x16x32_bf16 v[134:137], v[58:61], v[200:203], 0
	v_mfma_f32_16x16x32_bf16 v[130:133], v[70:73], v[200:203], 0
	v_mfma_f32_16x16x32_bf16 v[118:121], v[58:61], v[228:231], 0
	v_mfma_f32_16x16x32_bf16 v[114:117], v[70:73], v[228:231], 0
	v_mfma_f32_16x16x32_bf16 v[166:169], v[66:69], v[188:191], v[166:169]
	v_mfma_f32_16x16x32_bf16 v[162:165], v[74:77], v[188:191], v[162:165]
	v_mfma_f32_16x16x32_bf16 v[150:153], v[66:69], v[196:199], v[150:153]
	v_mfma_f32_16x16x32_bf16 v[146:149], v[74:77], v[196:199], v[146:149]
	v_mfma_f32_16x16x32_bf16 v[134:137], v[66:69], v[224:227], v[134:137]
	v_mfma_f32_16x16x32_bf16 v[130:133], v[74:77], v[224:227], v[130:133]
	v_mfma_f32_16x16x32_bf16 v[118:121], v[66:69], v[232:235], v[118:121]
	v_mfma_f32_16x16x32_bf16 v[114:117], v[74:77], v[232:235], v[114:117]
	v_mfma_f32_16x16x32_bf16 v[158:161], v[90:93], v[184:187], 0
	v_mfma_f32_16x16x32_bf16 v[154:157], v[98:101], v[184:187], 0
	v_mfma_f32_16x16x32_bf16 v[142:145], v[90:93], v[192:195], 0
	v_mfma_f32_16x16x32_bf16 v[138:141], v[98:101], v[192:195], 0
	v_mfma_f32_16x16x32_bf16 v[126:129], v[90:93], v[200:203], 0
	v_mfma_f32_16x16x32_bf16 v[122:125], v[98:101], v[200:203], 0
	v_mfma_f32_16x16x32_bf16 v[110:113], v[90:93], v[228:231], 0
	v_mfma_f32_16x16x32_bf16 v[106:109], v[98:101], v[228:231], 0
	v_mfma_f32_16x16x32_bf16 v[158:161], v[94:97], v[188:191], v[158:161]
	v_mfma_f32_16x16x32_bf16 v[154:157], v[102:105], v[188:191], v[154:157]
	v_mfma_f32_16x16x32_bf16 v[142:145], v[94:97], v[196:199], v[142:145]
	v_mfma_f32_16x16x32_bf16 v[138:141], v[102:105], v[196:199], v[138:141]
	v_mfma_f32_16x16x32_bf16 v[126:129], v[94:97], v[224:227], v[126:129]
	v_mfma_f32_16x16x32_bf16 v[122:125], v[102:105], v[224:227], v[122:125]
	v_mfma_f32_16x16x32_bf16 v[110:113], v[94:97], v[232:235], v[110:113]
	v_mfma_f32_16x16x32_bf16 v[106:109], v[102:105], v[232:235], v[106:109]
	s_barrier
	s_add_i32 s78, s91, s11
	v_lshl_add_u64 v[172:173], s[80:81], 0, v[2:3]
	s_mov_b32 m0, s78
	ds_read_b128 v[184:187], v222 offset:16384
	ds_read_b128 v[188:191], v222 offset:17408
	ds_read_b128 v[192:195], v222 offset:18432
	ds_read_b128 v[196:199], v222 offset:19456
	ds_read_b128 v[200:203], v222 offset:20480
	ds_read_b128 v[224:227], v222 offset:21504
	ds_read_b128 v[228:231], v222 offset:22528
	ds_read_b128 v[232:235], v222 offset:23552
	global_load_lds_dwordx4 v[172:173], off
	s_add_i32 m0, s78, 0x2000
	v_lshl_add_u64 v[236:237], s[80:81], 0, v[178:179]
	s_add_u32 s80, s80, s96
	s_addc_u32 s81, s81, 0
	s_add_i32 s75, s75, s11
	global_load_lds_dwordx4 v[236:237], off
	v_lshl_add_u64 v[238:239], s[80:81], 0, v[2:3]
	s_mov_b32 m0, s75
	v_lshl_add_u64 v[240:241], s[80:81], 0, v[178:179]
	global_load_lds_dwordx4 v[238:239], off
	s_add_i32 m0, s75, 0x2000
	v_lshl_add_u64 v[244:245], s[6:7], 0, v[4:5]
	global_load_lds_dwordx4 v[240:241], off
	s_mov_b32 m0, s24
	v_lshl_add_u64 v[246:247], s[6:7], 0, v[176:177]
	global_load_lds_dwordx4 v[244:245], off
	s_mov_b32 m0, s25
	s_nop 0
	global_load_lds_dwordx4 v[246:247], off
	s_waitcnt vmcnt(8)
	s_waitcnt lgkmcnt(0)
	s_barrier
; #define PG8_STAGE(bufoff, gbase, voff) do { _Pragma("unroll") for (int _i = 0; _i < 2; ++_i) \
;         __builtin_amdgcn_global_load_lds((const unsigned*)((const char*)(gbase) + (voff)[_i]), (LAS unsigned*)(lds + (bufoff) + ldsw + _i * 8192), 16, 0, 0); } while (0)
; #define PG8_LDA(dst, b, h) do { _Pragma("unroll") for (int m = 0; m < 4; ++m) _Pragma("unroll") for (int k = 0; k < 2; ++k) dst[m][k] = *(const LAS bf16x8*)(lds + PG8_SA(b, h) + aoff + m * 2048 + k * 1024); } while (0)
; #define PG8_LDB(dst, b, h) do { _Pragma("unroll") for (int n = 0; n < 2; ++n) _Pragma("unroll") for (int k = 0; k < 2; ++k) dst[n][k] = *(const LAS bf16x8*)(lds + PG8_SB(b, h) + boff + n * 2048 + k * 1024); } while (0)
; #define PG8_MMA(ai, bj, At, Bt) do { __builtin_amdgcn_s_setprio(1); _Pragma("unroll") for (int m = 0; m < 4; ++m) _Pragma("unroll") for (int n = 0; n < 2; ++n) _Pragma("unroll") for (int k = 0; k < 2; ++k) \
;         acc[ai][bj][m][n] = __builtin_amdgcn_mfma_f32_16x16x32_bf16(Bt[n][k], At[m][k], acc[ai][bj][m][n], 0, 0, 0); __builtin_amdgcn_s_setprio(0); } while (0)
; #define PG8_WAIT_V(n) asm volatile("s_waitcnt vmcnt(" #n ")" ::: "memory")
; #define PG8_WAIT_L(n) asm volatile("s_waitcnt lgkmcnt(" #n ")" ::: "memory")
; #define PG8_BAR __builtin_amdgcn_s_barrier()
; #define PG8_SCHED __builtin_amdgcn_sched_barrier(0)
; template <class Epi, bool ALIGN_EPI = true>
; __device__ __forceinline__ void gemm_phase(LAS unsigned char* lds, const Gemm g, const StaticOrder& S, const Epi& E) {
;     ...
;             PG8_WAIT_V(8); PG8_WAIT_L(0); PG8_BAR; PG8_MMA(1, 0, At, B0); PG8_MMA(1, 1, At, B1); PG8_BAR; PG8_SCHED;
;             PG8_LDB(B0, 1, 0); PG8_LDB(B1, 1, 1); PG8_SCHED; PG8_LDA(At, 1, 0); PG8_STAGE(PG8_SA(0, 1), a2 + hsA, voffA);
;             PG8_WAIT_V(8); PG8_WAIT_L(0); PG8_BAR; PG8_MMA(0, 0, At, B0); PG8_MMA(0, 1, At, B1); PG8_BAR; PG8_SCHED;
	s_waitcnt lgkmcnt(0)
	v_mfma_f32_16x16x32_bf16 v[86:89], v[58:61], v[184:187], 0
	v_mfma_f32_16x16x32_bf16 v[82:85], v[70:73], v[184:187], 0
	v_mfma_f32_16x16x32_bf16 v[54:57], v[58:61], v[192:195], 0
	v_mfma_f32_16x16x32_bf16 v[50:53], v[70:73], v[192:195], 0
	v_mfma_f32_16x16x32_bf16 v[38:41], v[58:61], v[200:203], 0
	v_mfma_f32_16x16x32_bf16 v[34:37], v[70:73], v[200:203], 0
	v_mfma_f32_16x16x32_bf16 v[22:25], v[58:61], v[228:231], 0
	v_mfma_f32_16x16x32_bf16 v[18:21], v[70:73], v[228:231], 0
	v_mfma_f32_16x16x32_bf16 v[86:89], v[66:69], v[188:191], v[86:89]
	v_mfma_f32_16x16x32_bf16 v[82:85], v[74:77], v[188:191], v[82:85]
	v_mfma_f32_16x16x32_bf16 v[54:57], v[66:69], v[196:199], v[54:57]
	v_mfma_f32_16x16x32_bf16 v[50:53], v[74:77], v[196:199], v[50:53]
	v_mfma_f32_16x16x32_bf16 v[38:41], v[66:69], v[224:227], v[38:41]
	v_mfma_f32_16x16x32_bf16 v[34:37], v[74:77], v[224:227], v[34:37]
	v_mfma_f32_16x16x32_bf16 v[22:25], v[66:69], v[232:235], v[22:25]
	v_mfma_f32_16x16x32_bf16 v[18:21], v[74:77], v[232:235], v[18:21]
	v_mfma_f32_16x16x32_bf16 v[62:65], v[98:101], v[184:187], 0
	v_mfma_f32_16x16x32_bf16 v[46:49], v[90:93], v[192:195], 0
	v_mfma_f32_16x16x32_bf16 v[42:45], v[98:101], v[192:195], 0
	v_mfma_f32_16x16x32_bf16 v[30:33], v[90:93], v[200:203], 0
	v_mfma_f32_16x16x32_bf16 v[26:29], v[98:101], v[200:203], 0
	v_mfma_f32_16x16x32_bf16 v[14:17], v[90:93], v[228:231], 0
	v_mfma_f32_16x16x32_bf16 v[10:13], v[98:101], v[228:231], 0
	v_mfma_f32_16x16x32_bf16 v[58:61], v[90:93], v[184:187], 0
	v_mfma_f32_16x16x32_bf16 v[62:65], v[102:105], v[188:191], v[62:65]
	v_mfma_f32_16x16x32_bf16 v[46:49], v[94:97], v[196:199], v[46:49]
	v_mfma_f32_16x16x32_bf16 v[42:45], v[102:105], v[196:199], v[42:45]
	v_mfma_f32_16x16x32_bf16 v[30:33], v[94:97], v[224:227], v[30:33]
	v_mfma_f32_16x16x32_bf16 v[26:29], v[102:105], v[224:227], v[26:29]
	v_mfma_f32_16x16x32_bf16 v[14:17], v[94:97], v[232:235], v[14:17]
	v_mfma_f32_16x16x32_bf16 v[10:13], v[102:105], v[232:235], v[10:13]
	v_mfma_f32_16x16x32_bf16 v[58:61], v[94:97], v[188:191], v[58:61]
	s_barrier
	s_add_i32 s75, 0, 0x18000
	s_add_i32 s78, 0, 0x1c000
	v_add_u32_e32 v78, s75, v221
	v_add_u32_e32 v102, s78, v221
	ds_read_b128 v[66:69], v78
	ds_read_b128 v[70:73], v78 offset:1024
	ds_read_b128 v[74:77], v78 offset:2048
	ds_read_b128 v[78:81], v78 offset:3072
	ds_read_b128 v[90:93], v102
	ds_read_b128 v[94:97], v102 offset:1024
	ds_read_b128 v[98:101], v102 offset:2048
	ds_read_b128 v[102:105], v102 offset:3072
	s_add_u32 s6, s6, s14
	s_addc_u32 s7, s7, 0
	s_mov_b32 m0, s26
	v_lshl_add_u64 v[248:249], s[6:7], 0, v[4:5]
	ds_read_b128 v[184:187], v222 offset:32768
	ds_read_b128 v[188:191], v222 offset:33792
	ds_read_b128 v[192:195], v222 offset:34816
	ds_read_b128 v[196:199], v222 offset:35840
	ds_read_b128 v[200:203], v222 offset:36864
	ds_read_b128 v[224:227], v222 offset:37888
	ds_read_b128 v[228:231], v222 offset:38912
	ds_read_b128 v[232:235], v222 offset:39936
	global_load_lds_dwordx4 v[248:249], off
	v_lshl_add_u64 v[248:249], s[6:7], 0, v[176:177]
	s_mov_b32 m0, s36
	s_nop 0
	global_load_lds_dwordx4 v[248:249], off
	s_waitcnt vmcnt(8)
	s_waitcnt lgkmcnt(0)
	s_barrier
	s_waitcnt lgkmcnt(0)
	v_mfma_f32_16x16x32_bf16 v[166:169], v[66:69], v[184:187], v[166:169]
	v_mfma_f32_16x16x32_bf16 v[162:165], v[74:77], v[184:187], v[162:165]
	v_mfma_f32_16x16x32_bf16 v[150:153], v[66:69], v[192:195], v[150:153]
	v_mfma_f32_16x16x32_bf16 v[146:149], v[74:77], v[192:195], v[146:149]
	v_mfma_f32_16x16x32_bf16 v[134:137], v[66:69], v[200:203], v[134:137]
	v_mfma_f32_16x16x32_bf16 v[130:133], v[74:77], v[200:203], v[130:133]
	v_mfma_f32_16x16x32_bf16 v[118:121], v[66:69], v[228:231], v[118:121]
	v_mfma_f32_16x16x32_bf16 v[114:117], v[74:77], v[228:231], v[114:117]
	v_mfma_f32_16x16x32_bf16 v[166:169], v[70:73], v[188:191], v[166:169]
	v_mfma_f32_16x16x32_bf16 v[162:165], v[78:81], v[188:191], v[162:165]
	v_mfma_f32_16x16x32_bf16 v[150:153], v[70:73], v[196:199], v[150:153]
	v_mfma_f32_16x16x32_bf16 v[146:149], v[78:81], v[196:199], v[146:149]
	v_mfma_f32_16x16x32_bf16 v[134:137], v[70:73], v[224:227], v[134:137]
	v_mfma_f32_16x16x32_bf16 v[130:133], v[78:81], v[224:227], v[130:133]
	v_mfma_f32_16x16x32_bf16 v[118:121], v[70:73], v[232:235], v[118:121]
	v_mfma_f32_16x16x32_bf16 v[114:117], v[78:81], v[232:235], v[114:117]
	v_mfma_f32_16x16x32_bf16 v[158:161], v[90:93], v[184:187], v[158:161]
	v_mfma_f32_16x16x32_bf16 v[154:157], v[98:101], v[184:187], v[154:157]
	v_mfma_f32_16x16x32_bf16 v[142:145], v[90:93], v[192:195], v[142:145]
	v_mfma_f32_16x16x32_bf16 v[138:141], v[98:101], v[192:195], v[138:141]
	v_mfma_f32_16x16x32_bf16 v[126:129], v[90:93], v[200:203], v[126:129]
	v_mfma_f32_16x16x32_bf16 v[122:125], v[98:101], v[200:203], v[122:125]
	v_mfma_f32_16x16x32_bf16 v[110:113], v[90:93], v[228:231], v[110:113]
	v_mfma_f32_16x16x32_bf16 v[106:109], v[98:101], v[228:231], v[106:109]
	v_mfma_f32_16x16x32_bf16 v[158:161], v[94:97], v[188:191], v[158:161]
	v_mfma_f32_16x16x32_bf16 v[154:157], v[102:105], v[188:191], v[154:157]
	v_mfma_f32_16x16x32_bf16 v[142:145], v[94:97], v[196:199], v[142:145]
	v_mfma_f32_16x16x32_bf16 v[138:141], v[102:105], v[196:199], v[138:141]
	v_mfma_f32_16x16x32_bf16 v[126:129], v[94:97], v[224:227], v[126:129]
	v_mfma_f32_16x16x32_bf16 v[122:125], v[102:105], v[224:227], v[122:125]
	v_mfma_f32_16x16x32_bf16 v[110:113], v[94:97], v[232:235], v[110:113]
	v_mfma_f32_16x16x32_bf16 v[106:109], v[102:105], v[232:235], v[106:109]
	s_barrier
; #define PG8_STAGE(bufoff, gbase, voff) do { _Pragma("unroll") for (int _i = 0; _i < 2; ++_i) \
;         __builtin_amdgcn_global_load_lds((const unsigned*)((const char*)(gbase) + (voff)[_i]), (LAS unsigned*)(lds + (bufoff) + ldsw + _i * 8192), 16, 0, 0); } while (0)
; #define PG8_LDA(dst, b, h) do { _Pragma("unroll") for (int m = 0; m < 4; ++m) _Pragma("unroll") for (int k = 0; k < 2; ++k) dst[m][k] = *(const LAS bf16x8*)(lds + PG8_SA(b, h) + aoff + m * 2048 + k * 1024); } while (0)
; #define PG8_MMA(ai, bj, At, Bt) do { __builtin_amdgcn_s_setprio(1); _Pragma("unroll") for (int m = 0; m < 4; ++m) _Pragma("unroll") for (int n = 0; n < 2; ++n) _Pragma("unroll") for (int k = 0; k < 2; ++k) \
;         acc[ai][bj][m][n] = __builtin_amdgcn_mfma_f32_16x16x32_bf16(Bt[n][k], At[m][k], acc[ai][bj][m][n], 0, 0, 0); __builtin_amdgcn_s_setprio(0); } while (0)
; #define PG8_WAIT_V(n) asm volatile("s_waitcnt vmcnt(" #n ")" ::: "memory")
; #define PG8_WAIT_L(n) asm volatile("s_waitcnt lgkmcnt(" #n ")" ::: "memory")
; #define PG8_BAR __builtin_amdgcn_s_barrier()
; #define PG8_SCHED __builtin_amdgcn_sched_barrier(0)
; template <class Epi, bool ALIGN_EPI = true>
; __device__ __forceinline__ void gemm_phase(LAS unsigned char* lds, const Gemm g, const StaticOrder& S, const Epi& E) {
;     ...
;             PG8_LDA(At, 1, 1); PG8_STAGE(PG8_SB(1, 0), b3, voffB); PG8_STAGE(PG8_SB(1, 1), b3 + hsB, voffB); PG8_STAGE(PG8_SA(1, 0), a3, voffA);
;             PG8_WAIT_V(8); PG8_WAIT_L(0); PG8_BAR; PG8_MMA(1, 0, At, B0); PG8_MMA(1, 1, At, B1); PG8_BAR; PG8_SCHED;
;         }
	s_add_i32 s6, s75, s11
	v_lshl_add_u64 v[172:173], v[172:173], 0, s[70:71]
	s_mov_b32 m0, s6
	ds_read_b128 v[184:187], v222 offset:49152
	ds_read_b128 v[188:191], v222 offset:50176
	ds_read_b128 v[192:195], v222 offset:51200
	ds_read_b128 v[196:199], v222 offset:52224
	ds_read_b128 v[200:203], v222 offset:53248
	ds_read_b128 v[224:227], v222 offset:54272
	ds_read_b128 v[228:231], v222 offset:55296
	ds_read_b128 v[232:235], v222 offset:56320
	global_load_lds_dwordx4 v[172:173], off
	v_lshl_add_u64 v[172:173], v[236:237], 0, s[70:71]
	s_add_i32 m0, s6, 0x2000
	s_add_i32 s6, s78, s11
	global_load_lds_dwordx4 v[172:173], off
	v_lshl_add_u64 v[172:173], v[238:239], 0, s[70:71]
	s_mov_b32 m0, s6
	s_nop 0
	global_load_lds_dwordx4 v[172:173], off
	v_lshl_add_u64 v[172:173], v[240:241], 0, s[70:71]
	s_add_i32 m0, s6, 0x2000
	s_nop 0
	global_load_lds_dwordx4 v[172:173], off
	v_lshl_add_u64 v[172:173], v[244:245], 0, s[70:71]
	s_mov_b32 m0, s69
	s_nop 0
	global_load_lds_dwordx4 v[172:173], off
	v_lshl_add_u64 v[172:173], v[246:247], 0, s[70:71]
	s_mov_b32 m0, s73
	s_nop 0
	global_load_lds_dwordx4 v[172:173], off
	s_waitcnt vmcnt(8)
	s_waitcnt lgkmcnt(0)
	s_barrier
	s_waitcnt lgkmcnt(0)
	v_mfma_f32_16x16x32_bf16 v[86:89], v[66:69], v[184:187], v[86:89]
	v_mfma_f32_16x16x32_bf16 v[82:85], v[74:77], v[184:187], v[82:85]
	v_mfma_f32_16x16x32_bf16 v[54:57], v[66:69], v[192:195], v[54:57]
	v_mfma_f32_16x16x32_bf16 v[50:53], v[74:77], v[192:195], v[50:53]
	v_mfma_f32_16x16x32_bf16 v[38:41], v[66:69], v[200:203], v[38:41]
	v_mfma_f32_16x16x32_bf16 v[34:37], v[74:77], v[200:203], v[34:37]
	v_mfma_f32_16x16x32_bf16 v[22:25], v[66:69], v[228:231], v[22:25]
	v_mfma_f32_16x16x32_bf16 v[18:21], v[74:77], v[228:231], v[18:21]
	v_mfma_f32_16x16x32_bf16 v[86:89], v[70:73], v[188:191], v[86:89]
	v_mfma_f32_16x16x32_bf16 v[82:85], v[78:81], v[188:191], v[82:85]
	v_mfma_f32_16x16x32_bf16 v[54:57], v[70:73], v[196:199], v[54:57]
	v_mfma_f32_16x16x32_bf16 v[50:53], v[78:81], v[196:199], v[50:53]
	v_mfma_f32_16x16x32_bf16 v[38:41], v[70:73], v[224:227], v[38:41]
	v_mfma_f32_16x16x32_bf16 v[34:37], v[78:81], v[224:227], v[34:37]
	v_mfma_f32_16x16x32_bf16 v[22:25], v[70:73], v[232:235], v[22:25]
	v_mfma_f32_16x16x32_bf16 v[18:21], v[78:81], v[232:235], v[18:21]
	v_mfma_f32_16x16x32_bf16 v[58:61], v[90:93], v[184:187], v[58:61]
	v_mfma_f32_16x16x32_bf16 v[78:81], v[94:97], v[188:191], v[58:61]
	v_mfma_f32_16x16x32_bf16 v[58:61], v[98:101], v[184:187], v[62:65]
	v_mfma_f32_16x16x32_bf16 v[46:49], v[90:93], v[192:195], v[46:49]
	v_mfma_f32_16x16x32_bf16 v[42:45], v[98:101], v[192:195], v[42:45]
	v_mfma_f32_16x16x32_bf16 v[30:33], v[90:93], v[200:203], v[30:33]
	v_mfma_f32_16x16x32_bf16 v[26:29], v[98:101], v[200:203], v[26:29]
	v_mfma_f32_16x16x32_bf16 v[14:17], v[90:93], v[228:231], v[14:17]
	v_mfma_f32_16x16x32_bf16 v[10:13], v[98:101], v[228:231], v[10:13]
	v_mfma_f32_16x16x32_bf16 v[62:65], v[102:105], v[188:191], v[58:61]
	v_mfma_f32_16x16x32_bf16 v[46:49], v[94:97], v[196:199], v[46:49]
	v_mfma_f32_16x16x32_bf16 v[42:45], v[102:105], v[196:199], v[42:45]
	v_mfma_f32_16x16x32_bf16 v[30:33], v[94:97], v[224:227], v[30:33]
	v_mfma_f32_16x16x32_bf16 v[26:29], v[102:105], v[224:227], v[26:29]
	v_mfma_f32_16x16x32_bf16 v[14:17], v[94:97], v[232:235], v[14:17]
	v_mfma_f32_16x16x32_bf16 v[10:13], v[102:105], v[232:235], v[10:13]
	s_barrier
	s_add_u32 s0, s0, 0x100
	s_addc_u32 s1, s1, 0
	s_add_u32 s8, s8, 0x100
	s_addc_u32 s9, s9, 0
	s_cmp_ge_u32 s74, s95
	s_mov_b32 s6, s74
	s_cbranch_scc1 .Lpeel_exit_259

; #define PG8_BAR __builtin_amdgcn_s_barrier()
; template <class Epi, bool ALIGN_EPI = true>
; __device__ __forceinline__ void gemm_phase(LAS unsigned char* lds, const Gemm g, const StaticOrder& S, const Epi& E) {
;     ...
;         if constexpr (ALIGN_EPI) { if (wr == 0) PG8_BAR; }
;         if constexpr (!Epi::AFTER_DRAIN) E.fast(acc, cur, wr, wc, fr, fq, rsc);
;         if (!has_next) break;
.Lpeel_exit_259:
	s_setprio 0
	v_readlane_b32 s0, v255, 0
	v_readlane_b32 s1, v255, 1
	s_and_b64 vcc, exec, s[0:1]
	s_cbranch_vccz .LBB0_262
	s_barrier

; #define PG8_STAGE(bufoff, gbase, voff) do { _Pragma("unroll") for (int _i = 0; _i < 2; ++_i) \
;         __builtin_amdgcn_global_load_lds((const unsigned*)((const char*)(gbase) + (voff)[_i]), (LAS unsigned*)(lds + (bufoff) + ldsw + _i * 8192), 16, 0, 0); } while (0)
; #define PG8_LDA(dst, b, h) do { _Pragma("unroll") for (int m = 0; m < 4; ++m) _Pragma("unroll") for (int k = 0; k < 2; ++k) dst[m][k] = *(const LAS bf16x8*)(lds + PG8_SA(b, h) + aoff + m * 2048 + k * 1024); } while (0)
; #define PG8_LDB(dst, b, h) do { _Pragma("unroll") for (int n = 0; n < 2; ++n) _Pragma("unroll") for (int k = 0; k < 2; ++k) dst[n][k] = *(const LAS bf16x8*)(lds + PG8_SB(b, h) + boff + n * 2048 + k * 1024); } while (0)
; #define PG8_MMA(ai, bj, At, Bt) do { __builtin_amdgcn_s_setprio(1); _Pragma("unroll") for (int m = 0; m < 4; ++m) _Pragma("unroll") for (int n = 0; n < 2; ++n) _Pragma("unroll") for (int k = 0; k < 2; ++k) \
;         acc[ai][bj][m][n] = __builtin_amdgcn_mfma_f32_16x16x32_bf16(Bt[n][k], At[m][k], acc[ai][bj][m][n], 0, 0, 0); __builtin_amdgcn_s_setprio(0); } while (0)
; #define PG8_WAIT_V(n) asm volatile("s_waitcnt vmcnt(" #n ")" ::: "memory")
; template <class Epi, bool ALIGN_EPI = true>
; __device__ __forceinline__ void gemm_phase(LAS unsigned char* lds, const Gemm g, const StaticOrder& S, const Epi& E) {
;     ...
;         for (int t = 0; t < nt; t += 2) {
;             const bool last = (t == nt - 2);
;             const char* a1 = cA + (size_t)(t + 1) * kstep;
;             const char* a2 = last ? nA : cA + (size_t)(t + 2) * kstep; const char* b2 = last ? nB : cB + (size_t)(t + 2) * kstep;
;             const char* a3 = a2 + kstep; const char* b3 = b2 + kstep;
;             PG8_LDB(B0, 0, 0); PG8_LDB(B1, 0, 1); PG8_SCHED; PG8_LDA(At, 0, 0); PG8_STAGE(PG8_SA(1, 1), a1 + hsA, voffA);
;             PG8_WAIT_V(8); PG8_WAIT_L(0); PG8_BAR; PG8_MMA(0, 0, At, B0); PG8_MMA(0, 1, At, B1); PG8_BAR; PG8_SCHED;
;             PG8_LDA(At, 0, 1); PG8_STAGE(PG8_SB(0, 0), b2, voffB); PG8_STAGE(PG8_SB(0, 1), b2 + hsB, voffB); PG8_STAGE(PG8_SA(0, 0), a2, voffA);
;     ...
; #pragma unroll
;         for (int a = 0; a < 2; ++a)
; #pragma unroll
;             for (int b = 0; b < 2; ++b)
; #pragma unroll
;                 for (int m = 0; m < 4; ++m)
; #pragma unroll
;                     for (int n = 0; n < 2; ++n) acc[a][b][m][n] = (f32x4){0.f, 0.f, 0.f, 0.f};
.LBB0_296:
	s_add_u32 s0, s86, 0x80
	s_addc_u32 s1, s87, 0
	s_add_u32 s86, s82, 0x100
	s_addc_u32 s87, s83, 0
	s_mov_b32 s82, 0
	v_readfirstlane_b32 vcc_lo, v0
	s_lshr_b32 vcc_lo, vcc_lo, 6
	s_cmp_ge_u32 vcc_lo, 4
	s_cbranch_scc0 .Lsp_skip_297
	s_setprio 1
.Lsp_skip_297:
	s_add_i32 vcc_lo, s82, 2
	s_add_u32 s80, s0, 0x80
	s_addc_u32 s81, s1, 0
	s_cmp_eq_u32 s72, s82
	s_cselect_b32 s83, s25, s81
	s_cselect_b32 s82, s24, s80
	v_add_u32_e32 v146, s91, v153
	s_cselect_b32 s81, s85, s87
	s_cselect_b32 s80, s84, s86
	s_add_i32 vcc_hi, 0, 0x14000
	ds_read_b128 v[156:159], v146
	ds_read_b128 v[160:163], v146 offset:1024
	ds_read_b128 v[164:167], v146 offset:2048
	ds_read_b128 v[176:179], v146 offset:3072
	v_add_u32_e32 v146, vcc_hi, v153
	ds_read_b128 v[180:183], v146
	ds_read_b128 v[184:187], v146 offset:1024
	ds_read_b128 v[188:191], v146 offset:2048
	ds_read_b128 v[192:195], v146 offset:3072
	v_lshl_add_u64 v[146:147], s[0:1], 0, v[142:143]
	s_add_i32 m0, s26, 0xc000
	ds_read_b128 v[196:199], v154
	ds_read_b128 v[200:203], v154 offset:1024
	ds_read_b128 v[220:223], v154 offset:2048
	ds_read_b128 v[224:227], v154 offset:3072
	ds_read_b128 v[228:231], v154 offset:4096
	ds_read_b128 v[232:235], v154 offset:5120
	ds_read_b128 v[236:239], v154 offset:6144
	ds_read_b128 v[244:247], v154 offset:7168
	global_load_lds_dwordx4 v[146:147], off
	v_lshl_add_u64 v[146:147], s[0:1], 0, v[144:145]
	s_add_i32 m0, s26, 0xe000
	s_nop 0
	global_load_lds_dwordx4 v[146:147], off
	s_waitcnt vmcnt(8)
	s_waitcnt lgkmcnt(0)
	s_barrier
	s_waitcnt lgkmcnt(0)
	v_mfma_f32_16x16x32_bf16 v[134:137], v[156:159], v[196:199], 0
	v_mfma_f32_16x16x32_bf16 v[130:133], v[164:167], v[196:199], 0
	v_mfma_f32_16x16x32_bf16 v[118:121], v[156:159], v[220:223], 0
	v_mfma_f32_16x16x32_bf16 v[114:117], v[164:167], v[220:223], 0
	v_mfma_f32_16x16x32_bf16 v[102:105], v[156:159], v[228:231], 0
	v_mfma_f32_16x16x32_bf16 v[98:101], v[164:167], v[228:231], 0
	v_mfma_f32_16x16x32_bf16 v[86:89], v[156:159], v[236:239], 0
	v_mfma_f32_16x16x32_bf16 v[82:85], v[164:167], v[236:239], 0
	v_mfma_f32_16x16x32_bf16 v[134:137], v[160:163], v[200:203], v[134:137]
	v_mfma_f32_16x16x32_bf16 v[130:133], v[176:179], v[200:203], v[130:133]
	v_mfma_f32_16x16x32_bf16 v[118:121], v[160:163], v[224:227], v[118:121]
	v_mfma_f32_16x16x32_bf16 v[114:117], v[176:179], v[224:227], v[114:117]
	v_mfma_f32_16x16x32_bf16 v[102:105], v[160:163], v[232:235], v[102:105]
	v_mfma_f32_16x16x32_bf16 v[98:101], v[176:179], v[232:235], v[98:101]
	v_mfma_f32_16x16x32_bf16 v[86:89], v[160:163], v[244:247], v[86:89]
	v_mfma_f32_16x16x32_bf16 v[82:85], v[176:179], v[244:247], v[82:85]
	v_mfma_f32_16x16x32_bf16 v[126:129], v[180:183], v[196:199], 0
	v_mfma_f32_16x16x32_bf16 v[122:125], v[188:191], v[196:199], 0
	v_mfma_f32_16x16x32_bf16 v[110:113], v[180:183], v[220:223], 0
	v_mfma_f32_16x16x32_bf16 v[106:109], v[188:191], v[220:223], 0
	v_mfma_f32_16x16x32_bf16 v[94:97], v[180:183], v[228:231], 0
	v_mfma_f32_16x16x32_bf16 v[90:93], v[188:191], v[228:231], 0
	v_mfma_f32_16x16x32_bf16 v[78:81], v[180:183], v[236:239], 0
	v_mfma_f32_16x16x32_bf16 v[74:77], v[188:191], v[236:239], 0
	v_mfma_f32_16x16x32_bf16 v[126:129], v[184:187], v[200:203], v[126:129]
	v_mfma_f32_16x16x32_bf16 v[122:125], v[192:195], v[200:203], v[122:125]
	v_mfma_f32_16x16x32_bf16 v[110:113], v[184:187], v[224:227], v[110:113]
	v_mfma_f32_16x16x32_bf16 v[106:109], v[192:195], v[224:227], v[106:109]
	v_mfma_f32_16x16x32_bf16 v[94:97], v[184:187], v[232:235], v[94:97]
	v_mfma_f32_16x16x32_bf16 v[90:93], v[192:195], v[232:235], v[90:93]
	v_mfma_f32_16x16x32_bf16 v[78:81], v[184:187], v[244:247], v[78:81]
	v_mfma_f32_16x16x32_bf16 v[74:77], v[192:195], v[244:247], v[74:77]
	s_barrier
	s_add_i32 s97, s91, s10
	v_lshl_add_u64 v[146:147], s[80:81], 0, v[2:3]
	s_mov_b32 m0, s97
	ds_read_b128 v[196:199], v154 offset:16384
	ds_read_b128 v[200:203], v154 offset:17408
	ds_read_b128 v[220:223], v154 offset:18432
	ds_read_b128 v[224:227], v154 offset:19456
	ds_read_b128 v[228:231], v154 offset:20480
	ds_read_b128 v[232:235], v154 offset:21504
	ds_read_b128 v[236:239], v154 offset:22528
	ds_read_b128 v[244:247], v154 offset:23552
	global_load_lds_dwordx4 v[146:147], off
	s_add_i32 m0, s97, 0x2000
	v_lshl_add_u64 v[150:151], s[80:81], 0, v[4:5]
	s_add_u32 s80, s80, s96
	s_addc_u32 s81, s81, 0
	s_add_i32 s97, vcc_hi, s10
	global_load_lds_dwordx4 v[150:151], off
	v_lshl_add_u64 v[168:169], s[80:81], 0, v[2:3]
	s_mov_b32 m0, s97
	v_lshl_add_u64 v[172:173], s[80:81], 0, v[4:5]
	global_load_lds_dwordx4 v[168:169], off
	s_add_i32 m0, s97, 0x2000
	v_lshl_add_u64 v[240:241], s[82:83], 0, v[140:141]
	global_load_lds_dwordx4 v[172:173], off
	s_mov_b32 m0, s26
	v_lshl_add_u64 v[248:249], s[82:83], 0, v[138:139]
	global_load_lds_dwordx4 v[240:241], off
	s_mov_b32 m0, s68
	s_nop 0
	global_load_lds_dwordx4 v[248:249], off
	s_waitcnt vmcnt(8)
	s_waitcnt lgkmcnt(0)
	s_barrier
; #define PG8_STAGE(bufoff, gbase, voff) do { _Pragma("unroll") for (int _i = 0; _i < 2; ++_i) \
;         __builtin_amdgcn_global_load_lds((const unsigned*)((const char*)(gbase) + (voff)[_i]), (LAS unsigned*)(lds + (bufoff) + ldsw + _i * 8192), 16, 0, 0); } while (0)
; #define PG8_LDA(dst, b, h) do { _Pragma("unroll") for (int m = 0; m < 4; ++m) _Pragma("unroll") for (int k = 0; k < 2; ++k) dst[m][k] = *(const LAS bf16x8*)(lds + PG8_SA(b, h) + aoff + m * 2048 + k * 1024); } while (0)
; #define PG8_LDB(dst, b, h) do { _Pragma("unroll") for (int n = 0; n < 2; ++n) _Pragma("unroll") for (int k = 0; k < 2; ++k) dst[n][k] = *(const LAS bf16x8*)(lds + PG8_SB(b, h) + boff + n * 2048 + k * 1024); } while (0)
; #define PG8_MMA(ai, bj, At, Bt) do { __builtin_amdgcn_s_setprio(1); _Pragma("unroll") for (int m = 0; m < 4; ++m) _Pragma("unroll") for (int n = 0; n < 2; ++n) _Pragma("unroll") for (int k = 0; k < 2; ++k) \
;         acc[ai][bj][m][n] = __builtin_amdgcn_mfma_f32_16x16x32_bf16(Bt[n][k], At[m][k], acc[ai][bj][m][n], 0, 0, 0); __builtin_amdgcn_s_setprio(0); } while (0)
; #define PG8_WAIT_V(n) asm volatile("s_waitcnt vmcnt(" #n ")" ::: "memory")
; #define PG8_WAIT_L(n) asm volatile("s_waitcnt lgkmcnt(" #n ")" ::: "memory")
; #define PG8_BAR __builtin_amdgcn_s_barrier()
; #define PG8_SCHED __builtin_amdgcn_sched_barrier(0)
; template <class Epi, bool ALIGN_EPI = true>
; __device__ __forceinline__ void gemm_phase(LAS unsigned char* lds, const Gemm g, const StaticOrder& S, const Epi& E) {
;     ...
;             PG8_WAIT_V(8); PG8_WAIT_L(0); PG8_BAR; PG8_MMA(1, 0, At, B0); PG8_MMA(1, 1, At, B1); PG8_BAR; PG8_SCHED;
;             PG8_LDB(B0, 1, 0); PG8_LDB(B1, 1, 1); PG8_SCHED; PG8_LDA(At, 1, 0); PG8_STAGE(PG8_SA(0, 1), a2 + hsA, voffA);
;             PG8_WAIT_V(8); PG8_WAIT_L(0); PG8_BAR; PG8_MMA(0, 0, At, B0); PG8_MMA(0, 1, At, B1); PG8_BAR; PG8_SCHED;
	s_waitcnt lgkmcnt(0)
	v_mfma_f32_16x16x32_bf16 v[70:73], v[156:159], v[196:199], 0
	v_mfma_f32_16x16x32_bf16 v[66:69], v[164:167], v[196:199], 0
	v_mfma_f32_16x16x32_bf16 v[54:57], v[156:159], v[220:223], 0
	v_mfma_f32_16x16x32_bf16 v[50:53], v[164:167], v[220:223], 0
	v_mfma_f32_16x16x32_bf16 v[38:41], v[156:159], v[228:231], 0
	v_mfma_f32_16x16x32_bf16 v[34:37], v[164:167], v[228:231], 0
	v_mfma_f32_16x16x32_bf16 v[22:25], v[156:159], v[236:239], 0
	v_mfma_f32_16x16x32_bf16 v[18:21], v[164:167], v[236:239], 0
	v_mfma_f32_16x16x32_bf16 v[70:73], v[160:163], v[200:203], v[70:73]
	v_mfma_f32_16x16x32_bf16 v[66:69], v[176:179], v[200:203], v[66:69]
	v_mfma_f32_16x16x32_bf16 v[54:57], v[160:163], v[224:227], v[54:57]
	v_mfma_f32_16x16x32_bf16 v[50:53], v[176:179], v[224:227], v[50:53]
	v_mfma_f32_16x16x32_bf16 v[38:41], v[160:163], v[232:235], v[38:41]
	v_mfma_f32_16x16x32_bf16 v[34:37], v[176:179], v[232:235], v[34:37]
	v_mfma_f32_16x16x32_bf16 v[22:25], v[160:163], v[244:247], v[22:25]
	v_mfma_f32_16x16x32_bf16 v[18:21], v[176:179], v[244:247], v[18:21]
	v_mfma_f32_16x16x32_bf16 v[62:65], v[180:183], v[196:199], 0
	v_mfma_f32_16x16x32_bf16 v[58:61], v[188:191], v[196:199], 0
	v_mfma_f32_16x16x32_bf16 v[46:49], v[180:183], v[220:223], 0
	v_mfma_f32_16x16x32_bf16 v[42:45], v[188:191], v[220:223], 0
	v_mfma_f32_16x16x32_bf16 v[30:33], v[180:183], v[228:231], 0
	v_mfma_f32_16x16x32_bf16 v[26:29], v[188:191], v[228:231], 0
	v_mfma_f32_16x16x32_bf16 v[14:17], v[180:183], v[236:239], 0
	v_mfma_f32_16x16x32_bf16 v[10:13], v[188:191], v[236:239], 0
	v_mfma_f32_16x16x32_bf16 v[62:65], v[184:187], v[200:203], v[62:65]
	v_mfma_f32_16x16x32_bf16 v[58:61], v[192:195], v[200:203], v[58:61]
	v_mfma_f32_16x16x32_bf16 v[46:49], v[184:187], v[224:227], v[46:49]
	v_mfma_f32_16x16x32_bf16 v[42:45], v[192:195], v[224:227], v[42:45]
	v_mfma_f32_16x16x32_bf16 v[30:33], v[184:187], v[232:235], v[30:33]
	v_mfma_f32_16x16x32_bf16 v[26:29], v[192:195], v[232:235], v[26:29]
	v_mfma_f32_16x16x32_bf16 v[14:17], v[184:187], v[244:247], v[14:17]
	v_mfma_f32_16x16x32_bf16 v[10:13], v[192:195], v[244:247], v[10:13]
	s_barrier
	s_add_i32 s97, 0, 0x18000
	v_add_u32_e32 v148, s97, v153
	s_add_i32 vcc_hi, 0, 0x1c000
	ds_read_b128 v[156:159], v148
	ds_read_b128 v[160:163], v148 offset:1024
	ds_read_b128 v[164:167], v148 offset:2048
	ds_read_b128 v[176:179], v148 offset:3072
	v_add_u32_e32 v148, vcc_hi, v153
	ds_read_b128 v[180:183], v148
	ds_read_b128 v[184:187], v148 offset:1024
	ds_read_b128 v[188:191], v148 offset:2048
	ds_read_b128 v[192:195], v148 offset:3072
	s_add_u32 s80, s82, s14
	s_addc_u32 s81, s83, 0
	s_mov_b32 m0, s69
	v_lshl_add_u64 v[250:251], s[80:81], 0, v[140:141]
	ds_read_b128 v[196:199], v154 offset:32768
	ds_read_b128 v[200:203], v154 offset:33792
	ds_read_b128 v[220:223], v154 offset:34816
	ds_read_b128 v[224:227], v154 offset:35840
	ds_read_b128 v[228:231], v154 offset:36864
	ds_read_b128 v[232:235], v154 offset:37888
	ds_read_b128 v[236:239], v154 offset:38912
	ds_read_b128 v[244:247], v154 offset:39936
	global_load_lds_dwordx4 v[250:251], off
	v_lshl_add_u64 v[250:251], s[80:81], 0, v[138:139]
	s_mov_b32 m0, s73
	s_nop 0
	global_load_lds_dwordx4 v[250:251], off
	s_waitcnt vmcnt(8)
	s_waitcnt lgkmcnt(0)
	s_barrier
	s_waitcnt lgkmcnt(0)
	v_mfma_f32_16x16x32_bf16 v[134:137], v[156:159], v[196:199], v[134:137]
	v_mfma_f32_16x16x32_bf16 v[130:133], v[164:167], v[196:199], v[130:133]
	v_mfma_f32_16x16x32_bf16 v[118:121], v[156:159], v[220:223], v[118:121]
	v_mfma_f32_16x16x32_bf16 v[114:117], v[164:167], v[220:223], v[114:117]
	v_mfma_f32_16x16x32_bf16 v[102:105], v[156:159], v[228:231], v[102:105]
	v_mfma_f32_16x16x32_bf16 v[98:101], v[164:167], v[228:231], v[98:101]
	v_mfma_f32_16x16x32_bf16 v[86:89], v[156:159], v[236:239], v[86:89]
	v_mfma_f32_16x16x32_bf16 v[82:85], v[164:167], v[236:239], v[82:85]
	v_mfma_f32_16x16x32_bf16 v[134:137], v[160:163], v[200:203], v[134:137]
	v_mfma_f32_16x16x32_bf16 v[130:133], v[176:179], v[200:203], v[130:133]
	v_mfma_f32_16x16x32_bf16 v[118:121], v[160:163], v[224:227], v[118:121]
	v_mfma_f32_16x16x32_bf16 v[114:117], v[176:179], v[224:227], v[114:117]
	v_mfma_f32_16x16x32_bf16 v[102:105], v[160:163], v[232:235], v[102:105]
	v_mfma_f32_16x16x32_bf16 v[98:101], v[176:179], v[232:235], v[98:101]
	v_mfma_f32_16x16x32_bf16 v[86:89], v[160:163], v[244:247], v[86:89]
	v_mfma_f32_16x16x32_bf16 v[82:85], v[176:179], v[244:247], v[82:85]
	v_mfma_f32_16x16x32_bf16 v[126:129], v[180:183], v[196:199], v[126:129]
	v_mfma_f32_16x16x32_bf16 v[122:125], v[188:191], v[196:199], v[122:125]
	v_mfma_f32_16x16x32_bf16 v[110:113], v[180:183], v[220:223], v[110:113]
	v_mfma_f32_16x16x32_bf16 v[106:109], v[188:191], v[220:223], v[106:109]
	v_mfma_f32_16x16x32_bf16 v[94:97], v[180:183], v[228:231], v[94:97]
	v_mfma_f32_16x16x32_bf16 v[90:93], v[188:191], v[228:231], v[90:93]
	v_mfma_f32_16x16x32_bf16 v[78:81], v[180:183], v[236:239], v[78:81]
	v_mfma_f32_16x16x32_bf16 v[74:77], v[188:191], v[236:239], v[74:77]
	v_mfma_f32_16x16x32_bf16 v[126:129], v[184:187], v[200:203], v[126:129]
	v_mfma_f32_16x16x32_bf16 v[122:125], v[192:195], v[200:203], v[122:125]
	v_mfma_f32_16x16x32_bf16 v[110:113], v[184:187], v[224:227], v[110:113]
	v_mfma_f32_16x16x32_bf16 v[106:109], v[192:195], v[224:227], v[106:109]
	v_mfma_f32_16x16x32_bf16 v[94:97], v[184:187], v[232:235], v[94:97]
	v_mfma_f32_16x16x32_bf16 v[90:93], v[192:195], v[232:235], v[90:93]
	v_mfma_f32_16x16x32_bf16 v[78:81], v[184:187], v[244:247], v[78:81]
	v_mfma_f32_16x16x32_bf16 v[74:77], v[192:195], v[244:247], v[74:77]
	s_barrier
; #define PG8_STAGE(bufoff, gbase, voff) do { _Pragma("unroll") for (int _i = 0; _i < 2; ++_i) \
;         __builtin_amdgcn_global_load_lds((const unsigned*)((const char*)(gbase) + (voff)[_i]), (LAS unsigned*)(lds + (bufoff) + ldsw + _i * 8192), 16, 0, 0); } while (0)
; #define PG8_LDA(dst, b, h) do { _Pragma("unroll") for (int m = 0; m < 4; ++m) _Pragma("unroll") for (int k = 0; k < 2; ++k) dst[m][k] = *(const LAS bf16x8*)(lds + PG8_SA(b, h) + aoff + m * 2048 + k * 1024); } while (0)
; #define PG8_MMA(ai, bj, At, Bt) do { __builtin_amdgcn_s_setprio(1); _Pragma("unroll") for (int m = 0; m < 4; ++m) _Pragma("unroll") for (int n = 0; n < 2; ++n) _Pragma("unroll") for (int k = 0; k < 2; ++k) \
;         acc[ai][bj][m][n] = __builtin_amdgcn_mfma_f32_16x16x32_bf16(Bt[n][k], At[m][k], acc[ai][bj][m][n], 0, 0, 0); __builtin_amdgcn_s_setprio(0); } while (0)
; #define PG8_WAIT_V(n) asm volatile("s_waitcnt vmcnt(" #n ")" ::: "memory")
; #define PG8_WAIT_L(n) asm volatile("s_waitcnt lgkmcnt(" #n ")" ::: "memory")
; #define PG8_BAR __builtin_amdgcn_s_barrier()
; #define PG8_SCHED __builtin_amdgcn_sched_barrier(0)
; template <class Epi, bool ALIGN_EPI = true>
; __device__ __forceinline__ void gemm_phase(LAS unsigned char* lds, const Gemm g, const StaticOrder& S, const Epi& E) {
;     ...
;             PG8_LDA(At, 1, 1); PG8_STAGE(PG8_SB(1, 0), b3, voffB); PG8_STAGE(PG8_SB(1, 1), b3 + hsB, voffB); PG8_STAGE(PG8_SA(1, 0), a3, voffA);
;             PG8_WAIT_V(8); PG8_WAIT_L(0); PG8_BAR; PG8_MMA(1, 0, At, B0); PG8_MMA(1, 1, At, B1); PG8_BAR; PG8_SCHED;
;         }
	s_add_i32 s80, s97, s10
	v_lshl_add_u64 v[146:147], v[146:147], 0, s[70:71]
	s_mov_b32 m0, s80
	ds_read_b128 v[196:199], v154 offset:49152
	ds_read_b128 v[200:203], v154 offset:50176
	ds_read_b128 v[220:223], v154 offset:51200
	ds_read_b128 v[224:227], v154 offset:52224
	ds_read_b128 v[228:231], v154 offset:53248
	ds_read_b128 v[232:235], v154 offset:54272
	ds_read_b128 v[236:239], v154 offset:55296
	ds_read_b128 v[244:247], v154 offset:56320
	global_load_lds_dwordx4 v[146:147], off
	v_lshl_add_u64 v[146:147], v[150:151], 0, s[70:71]
	s_add_i32 m0, s80, 0x2000
	s_add_i32 s80, vcc_hi, s10
	global_load_lds_dwordx4 v[146:147], off
	v_lshl_add_u64 v[146:147], v[168:169], 0, s[70:71]
	s_mov_b32 m0, s80
	s_nop 0
	global_load_lds_dwordx4 v[146:147], off
	v_lshl_add_u64 v[146:147], v[172:173], 0, s[70:71]
	s_add_i32 m0, s80, 0x2000
	s_nop 0
	global_load_lds_dwordx4 v[146:147], off
	v_lshl_add_u64 v[146:147], v[240:241], 0, s[70:71]
	s_mov_b32 m0, s93
	s_nop 0
	global_load_lds_dwordx4 v[146:147], off
	v_lshl_add_u64 v[146:147], v[248:249], 0, s[70:71]
	s_mov_b32 m0, s74
	s_nop 0
	global_load_lds_dwordx4 v[146:147], off
	s_waitcnt vmcnt(8)
	s_waitcnt lgkmcnt(0)
	s_barrier
	s_waitcnt lgkmcnt(0)
	v_mfma_f32_16x16x32_bf16 v[70:73], v[156:159], v[196:199], v[70:73]
	v_mfma_f32_16x16x32_bf16 v[66:69], v[164:167], v[196:199], v[66:69]
	v_mfma_f32_16x16x32_bf16 v[54:57], v[156:159], v[220:223], v[54:57]
	v_mfma_f32_16x16x32_bf16 v[50:53], v[164:167], v[220:223], v[50:53]
	v_mfma_f32_16x16x32_bf16 v[38:41], v[156:159], v[228:231], v[38:41]
	v_mfma_f32_16x16x32_bf16 v[34:37], v[164:167], v[228:231], v[34:37]
	v_mfma_f32_16x16x32_bf16 v[22:25], v[156:159], v[236:239], v[22:25]
	v_mfma_f32_16x16x32_bf16 v[18:21], v[164:167], v[236:239], v[18:21]
	v_mfma_f32_16x16x32_bf16 v[70:73], v[160:163], v[200:203], v[70:73]
	v_mfma_f32_16x16x32_bf16 v[66:69], v[176:179], v[200:203], v[66:69]
	v_mfma_f32_16x16x32_bf16 v[54:57], v[160:163], v[224:227], v[54:57]
	v_mfma_f32_16x16x32_bf16 v[50:53], v[176:179], v[224:227], v[50:53]
	v_mfma_f32_16x16x32_bf16 v[38:41], v[160:163], v[232:235], v[38:41]
	v_mfma_f32_16x16x32_bf16 v[34:37], v[176:179], v[232:235], v[34:37]
	v_mfma_f32_16x16x32_bf16 v[22:25], v[160:163], v[244:247], v[22:25]
	v_mfma_f32_16x16x32_bf16 v[18:21], v[176:179], v[244:247], v[18:21]
	v_mfma_f32_16x16x32_bf16 v[62:65], v[180:183], v[196:199], v[62:65]
	v_mfma_f32_16x16x32_bf16 v[58:61], v[188:191], v[196:199], v[58:61]
	v_mfma_f32_16x16x32_bf16 v[46:49], v[180:183], v[220:223], v[46:49]
	v_mfma_f32_16x16x32_bf16 v[42:45], v[188:191], v[220:223], v[42:45]
	v_mfma_f32_16x16x32_bf16 v[30:33], v[180:183], v[228:231], v[30:33]
	v_mfma_f32_16x16x32_bf16 v[26:29], v[188:191], v[228:231], v[26:29]
	v_mfma_f32_16x16x32_bf16 v[14:17], v[180:183], v[236:239], v[14:17]
	v_mfma_f32_16x16x32_bf16 v[10:13], v[188:191], v[236:239], v[10:13]
	v_mfma_f32_16x16x32_bf16 v[62:65], v[184:187], v[200:203], v[62:65]
	v_mfma_f32_16x16x32_bf16 v[58:61], v[192:195], v[200:203], v[58:61]
	v_mfma_f32_16x16x32_bf16 v[46:49], v[184:187], v[224:227], v[46:49]
	v_mfma_f32_16x16x32_bf16 v[42:45], v[192:195], v[224:227], v[42:45]
	v_mfma_f32_16x16x32_bf16 v[30:33], v[184:187], v[232:235], v[30:33]
	v_mfma_f32_16x16x32_bf16 v[26:29], v[192:195], v[232:235], v[26:29]
	v_mfma_f32_16x16x32_bf16 v[14:17], v[184:187], v[244:247], v[14:17]
	v_mfma_f32_16x16x32_bf16 v[10:13], v[192:195], v[244:247], v[10:13]
	s_barrier
	s_add_u32 s0, s0, 0x100
	s_addc_u32 s1, s1, 0
	s_add_u32 s86, s86, 0x100
	s_addc_u32 s87, s87, 0
	s_cmp_ge_u32 vcc_lo, s95
	s_mov_b32 s82, vcc_lo
	s_cbranch_scc1 .Lpeel_exit_297

; #define PG8_BAR __builtin_amdgcn_s_barrier()
; template <class Epi, bool ALIGN_EPI = true>
; __device__ __forceinline__ void gemm_phase(LAS unsigned char* lds, const Gemm g, const StaticOrder& S, const Epi& E) {
;     ...
;         if constexpr (ALIGN_EPI) { if (wr == 0) PG8_BAR; }
;         if constexpr (!Epi::AFTER_DRAIN) E.fast(acc, cur, wr, wc, fr, fq, rsc);
;         if (!has_next) break;
.Lpeel_exit_297:
	s_setprio 0
	s_and_b64 vcc, exec, s[22:23]
	s_cbranch_vccz .LBB0_300
	s_barrier

; #define PG8_STAGE(bufoff, gbase, voff) do { _Pragma("unroll") for (int _i = 0; _i < 2; ++_i) \
;         __builtin_amdgcn_global_load_lds((const unsigned*)((const char*)(gbase) + (voff)[_i]), (LAS unsigned*)(lds + (bufoff) + ldsw + _i * 8192), 16, 0, 0); } while (0)
; #define PG8_LDA(dst, b, h) do { _Pragma("unroll") for (int m = 0; m < 4; ++m) _Pragma("unroll") for (int k = 0; k < 2; ++k) dst[m][k] = *(const LAS bf16x8*)(lds + PG8_SA(b, h) + aoff + m * 2048 + k * 1024); } while (0)
; #define PG8_LDB(dst, b, h) do { _Pragma("unroll") for (int n = 0; n < 2; ++n) _Pragma("unroll") for (int k = 0; k < 2; ++k) dst[n][k] = *(const LAS bf16x8*)(lds + PG8_SB(b, h) + boff + n * 2048 + k * 1024); } while (0)
; #define PG8_MMA(ai, bj, At, Bt) do { __builtin_amdgcn_s_setprio(1); _Pragma("unroll") for (int m = 0; m < 4; ++m) _Pragma("unroll") for (int n = 0; n < 2; ++n) _Pragma("unroll") for (int k = 0; k < 2; ++k) \
;         acc[ai][bj][m][n] = __builtin_amdgcn_mfma_f32_16x16x32_bf16(Bt[n][k], At[m][k], acc[ai][bj][m][n], 0, 0, 0); __builtin_amdgcn_s_setprio(0); } while (0)
; #define PG8_WAIT_V(n) asm volatile("s_waitcnt vmcnt(" #n ")" ::: "memory")
; template <class Epi, bool ALIGN_EPI = true>
; __device__ __forceinline__ void gemm_phase(LAS unsigned char* lds, const Gemm g, const StaticOrder& S, const Epi& E) {
;     ...
;         for (int t = 0; t < nt; t += 2) {
;             const bool last = (t == nt - 2);
;             const char* a1 = cA + (size_t)(t + 1) * kstep;
;             const char* a2 = last ? nA : cA + (size_t)(t + 2) * kstep; const char* b2 = last ? nB : cB + (size_t)(t + 2) * kstep;
;             const char* a3 = a2 + kstep; const char* b3 = b2 + kstep;
;             PG8_LDB(B0, 0, 0); PG8_LDB(B1, 0, 1); PG8_SCHED; PG8_LDA(At, 0, 0); PG8_STAGE(PG8_SA(1, 1), a1 + hsA, voffA);
;             PG8_WAIT_V(8); PG8_WAIT_L(0); PG8_BAR; PG8_MMA(0, 0, At, B0); PG8_MMA(0, 1, At, B1); PG8_BAR; PG8_SCHED;
;             PG8_LDA(At, 0, 1); PG8_STAGE(PG8_SB(0, 0), b2, voffB); PG8_STAGE(PG8_SB(0, 1), b2 + hsB, voffB); PG8_STAGE(PG8_SA(0, 0), a2, voffA);
;     ...
; #pragma unroll
;         for (int a = 0; a < 2; ++a)
; #pragma unroll
;             for (int b = 0; b < 2; ++b)
; #pragma unroll
;                 for (int m = 0; m < 4; ++m)
; #pragma unroll
;                     for (int n = 0; n < 2; ++n) acc[a][b][m][n] = (f32x4){0.f, 0.f, 0.f, 0.f};
.LBB0_327:
	s_add_u32 s0, s84, 0x80
	s_addc_u32 s1, s85, 0
	s_add_u32 s3, s82, 0x100
	s_addc_u32 s10, s83, 0
	s_mov_b32 s11, 0
	v_readfirstlane_b32 s26, v0
	s_lshr_b32 s26, s26, 6
	s_cmp_ge_u32 s26, 4
	s_cbranch_scc0 .Lsp_skip_328
	s_setprio 1
.Lsp_skip_328:
	s_add_i32 s26, s11, 2
	s_add_u32 s69, s0, 0x80
	s_addc_u32 s74, s1, 0
	s_cmp_eq_u32 s72, s11
	s_cselect_b32 s83, s23, s74
	s_cselect_b32 s82, s22, s69
	v_add_u32_e32 v2, s91, v176
	s_cselect_b32 s75, s25, s10
	s_cselect_b32 s74, s24, s3
	s_add_i32 s11, 0, 0x14000
	ds_read_b128 v[138:141], v2
	ds_read_b128 v[142:145], v2 offset:1024
	ds_read_b128 v[146:149], v2 offset:2048
	ds_read_b128 v[150:153], v2 offset:3072
	v_add_u32_e32 v2, s11, v176
	ds_read_b128 v[164:167], v2
	ds_read_b128 v[178:181], v2 offset:1024
	ds_read_b128 v[182:185], v2 offset:2048
	ds_read_b128 v[186:189], v2 offset:3072
	v_lshl_add_u64 v[202:203], s[0:1], 0, v[160:161]
	s_add_i32 m0, s86, 0xc000
	ds_read_b128 v[190:193], v1
	ds_read_b128 v[194:197], v1 offset:1024
	ds_read_b128 v[198:201], v1 offset:2048
	ds_read_b128 v[220:223], v1 offset:3072
	ds_read_b128 v[224:227], v1 offset:4096
	ds_read_b128 v[228:231], v1 offset:5120
	ds_read_b128 v[232:235], v1 offset:6144
	ds_read_b128 v[236:239], v1 offset:7168
	global_load_lds_dwordx4 v[202:203], off
	v_lshl_add_u64 v[202:203], s[0:1], 0, v[162:163]
	s_add_i32 m0, s86, 0xe000
	s_nop 0
	global_load_lds_dwordx4 v[202:203], off
	s_waitcnt vmcnt(8)
	s_waitcnt lgkmcnt(0)
	s_barrier
	s_waitcnt lgkmcnt(0)
	v_mfma_f32_16x16x32_bf16 v[134:137], v[138:141], v[190:193], 0
	v_mfma_f32_16x16x32_bf16 v[130:133], v[146:149], v[190:193], 0
	v_mfma_f32_16x16x32_bf16 v[122:125], v[138:141], v[198:201], 0
	v_mfma_f32_16x16x32_bf16 v[114:117], v[146:149], v[198:201], 0
	v_mfma_f32_16x16x32_bf16 v[106:109], v[138:141], v[224:227], 0
	v_mfma_f32_16x16x32_bf16 v[98:101], v[146:149], v[224:227], 0
	v_mfma_f32_16x16x32_bf16 v[86:89], v[138:141], v[232:235], 0
	v_mfma_f32_16x16x32_bf16 v[82:85], v[146:149], v[232:235], 0
	v_mfma_f32_16x16x32_bf16 v[134:137], v[142:145], v[194:197], v[134:137]
	v_mfma_f32_16x16x32_bf16 v[130:133], v[150:153], v[194:197], v[130:133]
	v_mfma_f32_16x16x32_bf16 v[122:125], v[142:145], v[220:223], v[122:125]
	v_mfma_f32_16x16x32_bf16 v[114:117], v[150:153], v[220:223], v[114:117]
	v_mfma_f32_16x16x32_bf16 v[106:109], v[142:145], v[228:231], v[106:109]
	v_mfma_f32_16x16x32_bf16 v[98:101], v[150:153], v[228:231], v[98:101]
	v_mfma_f32_16x16x32_bf16 v[86:89], v[142:145], v[236:239], v[86:89]
	v_mfma_f32_16x16x32_bf16 v[82:85], v[150:153], v[236:239], v[82:85]
	v_mfma_f32_16x16x32_bf16 v[126:129], v[164:167], v[190:193], 0
	v_mfma_f32_16x16x32_bf16 v[118:121], v[182:185], v[190:193], 0
	v_mfma_f32_16x16x32_bf16 v[110:113], v[164:167], v[198:201], 0
	v_mfma_f32_16x16x32_bf16 v[102:105], v[182:185], v[198:201], 0
	v_mfma_f32_16x16x32_bf16 v[94:97], v[164:167], v[224:227], 0
	v_mfma_f32_16x16x32_bf16 v[90:93], v[182:185], v[224:227], 0
	v_mfma_f32_16x16x32_bf16 v[78:81], v[164:167], v[232:235], 0
	v_mfma_f32_16x16x32_bf16 v[74:77], v[182:185], v[232:235], 0
	v_mfma_f32_16x16x32_bf16 v[126:129], v[178:181], v[194:197], v[126:129]
	v_mfma_f32_16x16x32_bf16 v[118:121], v[186:189], v[194:197], v[118:121]
	v_mfma_f32_16x16x32_bf16 v[110:113], v[178:181], v[220:223], v[110:113]
	v_mfma_f32_16x16x32_bf16 v[102:105], v[186:189], v[220:223], v[102:105]
	v_mfma_f32_16x16x32_bf16 v[94:97], v[178:181], v[228:231], v[94:97]
	v_mfma_f32_16x16x32_bf16 v[90:93], v[186:189], v[228:231], v[90:93]
	v_mfma_f32_16x16x32_bf16 v[78:81], v[178:181], v[236:239], v[78:81]
	v_mfma_f32_16x16x32_bf16 v[74:77], v[186:189], v[236:239], v[74:77]
	s_barrier
	s_add_i32 s69, s91, s73
	v_lshl_add_u64 v[202:203], s[74:75], 0, v[154:155]
	s_mov_b32 m0, s69
	ds_read_b128 v[190:193], v1 offset:16384
	ds_read_b128 v[194:197], v1 offset:17408
	ds_read_b128 v[198:201], v1 offset:18432
	ds_read_b128 v[220:223], v1 offset:19456
	ds_read_b128 v[224:227], v1 offset:20480
	ds_read_b128 v[228:231], v1 offset:21504
	ds_read_b128 v[232:235], v1 offset:22528
	ds_read_b128 v[236:239], v1 offset:23552
	global_load_lds_dwordx4 v[202:203], off
	s_add_i32 m0, s69, 0x2000
	v_lshl_add_u64 v[240:241], s[74:75], 0, v[158:159]
	s_add_u32 s74, s74, s96
	s_addc_u32 s75, s75, 0
	s_add_i32 s11, s11, s73
	global_load_lds_dwordx4 v[240:241], off
	v_lshl_add_u64 v[244:245], s[74:75], 0, v[154:155]
	s_mov_b32 m0, s11
	v_lshl_add_u64 v[246:247], s[74:75], 0, v[158:159]
	global_load_lds_dwordx4 v[244:245], off
	s_add_i32 m0, s11, 0x2000
	v_lshl_add_u64 v[248:249], s[82:83], 0, v[4:5]
	global_load_lds_dwordx4 v[246:247], off
	s_mov_b32 m0, s86
	v_lshl_add_u64 v[250:251], s[82:83], 0, v[156:157]
	global_load_lds_dwordx4 v[248:249], off
	s_mov_b32 m0, s87
	s_nop 0
	global_load_lds_dwordx4 v[250:251], off
	s_waitcnt vmcnt(8)
	s_waitcnt lgkmcnt(0)
	s_barrier
; #define PG8_STAGE(bufoff, gbase, voff) do { _Pragma("unroll") for (int _i = 0; _i < 2; ++_i) \
;         __builtin_amdgcn_global_load_lds((const unsigned*)((const char*)(gbase) + (voff)[_i]), (LAS unsigned*)(lds + (bufoff) + ldsw + _i * 8192), 16, 0, 0); } while (0)
; #define PG8_LDA(dst, b, h) do { _Pragma("unroll") for (int m = 0; m < 4; ++m) _Pragma("unroll") for (int k = 0; k < 2; ++k) dst[m][k] = *(const LAS bf16x8*)(lds + PG8_SA(b, h) + aoff + m * 2048 + k * 1024); } while (0)
; #define PG8_LDB(dst, b, h) do { _Pragma("unroll") for (int n = 0; n < 2; ++n) _Pragma("unroll") for (int k = 0; k < 2; ++k) dst[n][k] = *(const LAS bf16x8*)(lds + PG8_SB(b, h) + boff + n * 2048 + k * 1024); } while (0)
; #define PG8_MMA(ai, bj, At, Bt) do { __builtin_amdgcn_s_setprio(1); _Pragma("unroll") for (int m = 0; m < 4; ++m) _Pragma("unroll") for (int n = 0; n < 2; ++n) _Pragma("unroll") for (int k = 0; k < 2; ++k) \
;         acc[ai][bj][m][n] = __builtin_amdgcn_mfma_f32_16x16x32_bf16(Bt[n][k], At[m][k], acc[ai][bj][m][n], 0, 0, 0); __builtin_amdgcn_s_setprio(0); } while (0)
; #define PG8_WAIT_V(n) asm volatile("s_waitcnt vmcnt(" #n ")" ::: "memory")
; #define PG8_WAIT_L(n) asm volatile("s_waitcnt lgkmcnt(" #n ")" ::: "memory")
; #define PG8_BAR __builtin_amdgcn_s_barrier()
; #define PG8_SCHED __builtin_amdgcn_sched_barrier(0)
; template <class Epi, bool ALIGN_EPI = true>
; __device__ __forceinline__ void gemm_phase(LAS unsigned char* lds, const Gemm g, const StaticOrder& S, const Epi& E) {
;     ...
;             PG8_WAIT_V(8); PG8_WAIT_L(0); PG8_BAR; PG8_MMA(1, 0, At, B0); PG8_MMA(1, 1, At, B1); PG8_BAR; PG8_SCHED;
;             PG8_LDB(B0, 1, 0); PG8_LDB(B1, 1, 1); PG8_SCHED; PG8_LDA(At, 1, 0); PG8_STAGE(PG8_SA(0, 1), a2 + hsA, voffA);
;             PG8_WAIT_V(8); PG8_WAIT_L(0); PG8_BAR; PG8_MMA(0, 0, At, B0); PG8_MMA(0, 1, At, B1); PG8_BAR; PG8_SCHED;
	s_waitcnt lgkmcnt(0)
	v_mfma_f32_16x16x32_bf16 v[70:73], v[138:141], v[190:193], 0
	v_mfma_f32_16x16x32_bf16 v[66:69], v[146:149], v[190:193], 0
	v_mfma_f32_16x16x32_bf16 v[58:61], v[138:141], v[198:201], 0
	v_mfma_f32_16x16x32_bf16 v[50:53], v[146:149], v[198:201], 0
	v_mfma_f32_16x16x32_bf16 v[42:45], v[138:141], v[224:227], 0
	v_mfma_f32_16x16x32_bf16 v[34:37], v[146:149], v[224:227], 0
	v_mfma_f32_16x16x32_bf16 v[22:25], v[138:141], v[232:235], 0
	v_mfma_f32_16x16x32_bf16 v[18:21], v[146:149], v[232:235], 0
	v_mfma_f32_16x16x32_bf16 v[70:73], v[142:145], v[194:197], v[70:73]
	v_mfma_f32_16x16x32_bf16 v[66:69], v[150:153], v[194:197], v[66:69]
	v_mfma_f32_16x16x32_bf16 v[58:61], v[142:145], v[220:223], v[58:61]
	v_mfma_f32_16x16x32_bf16 v[50:53], v[150:153], v[220:223], v[50:53]
	v_mfma_f32_16x16x32_bf16 v[42:45], v[142:145], v[228:231], v[42:45]
	v_mfma_f32_16x16x32_bf16 v[34:37], v[150:153], v[228:231], v[34:37]
	v_mfma_f32_16x16x32_bf16 v[22:25], v[142:145], v[236:239], v[22:25]
	v_mfma_f32_16x16x32_bf16 v[18:21], v[150:153], v[236:239], v[18:21]
	v_mfma_f32_16x16x32_bf16 v[62:65], v[164:167], v[190:193], 0
	v_mfma_f32_16x16x32_bf16 v[54:57], v[182:185], v[190:193], 0
	v_mfma_f32_16x16x32_bf16 v[46:49], v[164:167], v[198:201], 0
	v_mfma_f32_16x16x32_bf16 v[38:41], v[182:185], v[198:201], 0
	v_mfma_f32_16x16x32_bf16 v[30:33], v[164:167], v[224:227], 0
	v_mfma_f32_16x16x32_bf16 v[26:29], v[182:185], v[224:227], 0
	v_mfma_f32_16x16x32_bf16 v[14:17], v[164:167], v[232:235], 0
	v_mfma_f32_16x16x32_bf16 v[10:13], v[182:185], v[232:235], 0
	v_mfma_f32_16x16x32_bf16 v[62:65], v[178:181], v[194:197], v[62:65]
	v_mfma_f32_16x16x32_bf16 v[54:57], v[186:189], v[194:197], v[54:57]
	v_mfma_f32_16x16x32_bf16 v[46:49], v[178:181], v[220:223], v[46:49]
	v_mfma_f32_16x16x32_bf16 v[38:41], v[186:189], v[220:223], v[38:41]
	v_mfma_f32_16x16x32_bf16 v[30:33], v[178:181], v[228:231], v[30:33]
	v_mfma_f32_16x16x32_bf16 v[26:29], v[186:189], v[228:231], v[26:29]
	v_mfma_f32_16x16x32_bf16 v[14:17], v[178:181], v[236:239], v[14:17]
	v_mfma_f32_16x16x32_bf16 v[10:13], v[186:189], v[236:239], v[10:13]
	s_barrier
	s_add_i32 s11, 0, 0x18000
	v_add_u32_e32 v2, s11, v176
	s_add_i32 s69, 0, 0x1c000
	ds_read_b128 v[138:141], v2
	ds_read_b128 v[142:145], v2 offset:1024
	ds_read_b128 v[146:149], v2 offset:2048
	ds_read_b128 v[150:153], v2 offset:3072
	v_add_u32_e32 v2, s69, v176
	ds_read_b128 v[164:167], v2
	ds_read_b128 v[178:181], v2 offset:1024
	ds_read_b128 v[182:185], v2 offset:2048
	ds_read_b128 v[186:189], v2 offset:3072
	s_add_u32 s74, s82, s14
	s_addc_u32 s75, s83, 0
	s_mov_b32 m0, s88
	v_lshl_add_u64 v[172:173], s[74:75], 0, v[4:5]
	ds_read_b128 v[190:193], v1 offset:32768
	ds_read_b128 v[194:197], v1 offset:33792
	ds_read_b128 v[198:201], v1 offset:34816
	ds_read_b128 v[220:223], v1 offset:35840
	ds_read_b128 v[224:227], v1 offset:36864
	ds_read_b128 v[228:231], v1 offset:37888
	ds_read_b128 v[232:235], v1 offset:38912
	ds_read_b128 v[236:239], v1 offset:39936
	global_load_lds_dwordx4 v[172:173], off
	v_lshl_add_u64 v[172:173], s[74:75], 0, v[156:157]
	s_mov_b32 m0, s89
	s_nop 0
	global_load_lds_dwordx4 v[172:173], off
	s_waitcnt vmcnt(8)
	s_waitcnt lgkmcnt(0)
	s_barrier
	s_waitcnt lgkmcnt(0)
	v_mfma_f32_16x16x32_bf16 v[134:137], v[138:141], v[190:193], v[134:137]
	v_mfma_f32_16x16x32_bf16 v[130:133], v[146:149], v[190:193], v[130:133]
	v_mfma_f32_16x16x32_bf16 v[122:125], v[138:141], v[198:201], v[122:125]
	v_mfma_f32_16x16x32_bf16 v[114:117], v[146:149], v[198:201], v[114:117]
	v_mfma_f32_16x16x32_bf16 v[106:109], v[138:141], v[224:227], v[106:109]
	v_mfma_f32_16x16x32_bf16 v[98:101], v[146:149], v[224:227], v[98:101]
	v_mfma_f32_16x16x32_bf16 v[86:89], v[138:141], v[232:235], v[86:89]
	v_mfma_f32_16x16x32_bf16 v[82:85], v[146:149], v[232:235], v[82:85]
	v_mfma_f32_16x16x32_bf16 v[134:137], v[142:145], v[194:197], v[134:137]
	v_mfma_f32_16x16x32_bf16 v[130:133], v[150:153], v[194:197], v[130:133]
	v_mfma_f32_16x16x32_bf16 v[122:125], v[142:145], v[220:223], v[122:125]
	v_mfma_f32_16x16x32_bf16 v[114:117], v[150:153], v[220:223], v[114:117]
	v_mfma_f32_16x16x32_bf16 v[106:109], v[142:145], v[228:231], v[106:109]
	v_mfma_f32_16x16x32_bf16 v[98:101], v[150:153], v[228:231], v[98:101]
	v_mfma_f32_16x16x32_bf16 v[86:89], v[142:145], v[236:239], v[86:89]
	v_mfma_f32_16x16x32_bf16 v[82:85], v[150:153], v[236:239], v[82:85]
	v_mfma_f32_16x16x32_bf16 v[126:129], v[164:167], v[190:193], v[126:129]
	v_mfma_f32_16x16x32_bf16 v[118:121], v[182:185], v[190:193], v[118:121]
	v_mfma_f32_16x16x32_bf16 v[110:113], v[164:167], v[198:201], v[110:113]
	v_mfma_f32_16x16x32_bf16 v[102:105], v[182:185], v[198:201], v[102:105]
	v_mfma_f32_16x16x32_bf16 v[94:97], v[164:167], v[224:227], v[94:97]
	v_mfma_f32_16x16x32_bf16 v[90:93], v[182:185], v[224:227], v[90:93]
	v_mfma_f32_16x16x32_bf16 v[78:81], v[164:167], v[232:235], v[78:81]
	v_mfma_f32_16x16x32_bf16 v[74:77], v[182:185], v[232:235], v[74:77]
	v_mfma_f32_16x16x32_bf16 v[126:129], v[178:181], v[194:197], v[126:129]
	v_mfma_f32_16x16x32_bf16 v[118:121], v[186:189], v[194:197], v[118:121]
	v_mfma_f32_16x16x32_bf16 v[110:113], v[178:181], v[220:223], v[110:113]
	v_mfma_f32_16x16x32_bf16 v[102:105], v[186:189], v[220:223], v[102:105]
	v_mfma_f32_16x16x32_bf16 v[94:97], v[178:181], v[228:231], v[94:97]
	v_mfma_f32_16x16x32_bf16 v[90:93], v[186:189], v[228:231], v[90:93]
	v_mfma_f32_16x16x32_bf16 v[78:81], v[178:181], v[236:239], v[78:81]
	v_mfma_f32_16x16x32_bf16 v[74:77], v[186:189], v[236:239], v[74:77]
	s_barrier
; #define PG8_STAGE(bufoff, gbase, voff) do { _Pragma("unroll") for (int _i = 0; _i < 2; ++_i) \
;         __builtin_amdgcn_global_load_lds((const unsigned*)((const char*)(gbase) + (voff)[_i]), (LAS unsigned*)(lds + (bufoff) + ldsw + _i * 8192), 16, 0, 0); } while (0)
; #define PG8_LDA(dst, b, h) do { _Pragma("unroll") for (int m = 0; m < 4; ++m) _Pragma("unroll") for (int k = 0; k < 2; ++k) dst[m][k] = *(const LAS bf16x8*)(lds + PG8_SA(b, h) + aoff + m * 2048 + k * 1024); } while (0)
; #define PG8_MMA(ai, bj, At, Bt) do { __builtin_amdgcn_s_setprio(1); _Pragma("unroll") for (int m = 0; m < 4; ++m) _Pragma("unroll") for (int n = 0; n < 2; ++n) _Pragma("unroll") for (int k = 0; k < 2; ++k) \
;         acc[ai][bj][m][n] = __builtin_amdgcn_mfma_f32_16x16x32_bf16(Bt[n][k], At[m][k], acc[ai][bj][m][n], 0, 0, 0); __builtin_amdgcn_s_setprio(0); } while (0)
; #define PG8_WAIT_V(n) asm volatile("s_waitcnt vmcnt(" #n ")" ::: "memory")
; #define PG8_WAIT_L(n) asm volatile("s_waitcnt lgkmcnt(" #n ")" ::: "memory")
; #define PG8_BAR __builtin_amdgcn_s_barrier()
; #define PG8_SCHED __builtin_amdgcn_sched_barrier(0)
; template <class Epi, bool ALIGN_EPI = true>
; __device__ __forceinline__ void gemm_phase(LAS unsigned char* lds, const Gemm g, const StaticOrder& S, const Epi& E) {
;     ...
;             PG8_LDA(At, 1, 1); PG8_STAGE(PG8_SB(1, 0), b3, voffB); PG8_STAGE(PG8_SB(1, 1), b3 + hsB, voffB); PG8_STAGE(PG8_SA(1, 0), a3, voffA);
;             PG8_WAIT_V(8); PG8_WAIT_L(0); PG8_BAR; PG8_MMA(1, 0, At, B0); PG8_MMA(1, 1, At, B1); PG8_BAR; PG8_SCHED;
;         }
	s_add_i32 s11, s11, s73
	v_lshl_add_u64 v[172:173], v[202:203], 0, s[70:71]
	s_mov_b32 m0, s11
	ds_read_b128 v[190:193], v1 offset:49152
	ds_read_b128 v[194:197], v1 offset:50176
	ds_read_b128 v[198:201], v1 offset:51200
	ds_read_b128 v[220:223], v1 offset:52224
	ds_read_b128 v[224:227], v1 offset:53248
	ds_read_b128 v[228:231], v1 offset:54272
	ds_read_b128 v[232:235], v1 offset:55296
	ds_read_b128 v[236:239], v1 offset:56320
	global_load_lds_dwordx4 v[172:173], off
	v_lshl_add_u64 v[172:173], v[240:241], 0, s[70:71]
	s_add_i32 m0, s11, 0x2000
	s_add_i32 s11, s69, s73
	global_load_lds_dwordx4 v[172:173], off
	v_lshl_add_u64 v[172:173], v[244:245], 0, s[70:71]
	s_mov_b32 m0, s11
	s_nop 0
	global_load_lds_dwordx4 v[172:173], off
	v_lshl_add_u64 v[172:173], v[246:247], 0, s[70:71]
	s_add_i32 m0, s11, 0x2000
	s_nop 0
	global_load_lds_dwordx4 v[172:173], off
	v_lshl_add_u64 v[172:173], v[248:249], 0, s[70:71]
	s_mov_b32 m0, s7
	s_nop 0
	global_load_lds_dwordx4 v[172:173], off
	v_lshl_add_u64 v[172:173], v[250:251], 0, s[70:71]
	s_mov_b32 m0, s6
	s_nop 0
	global_load_lds_dwordx4 v[172:173], off
	s_waitcnt vmcnt(8)
	s_waitcnt lgkmcnt(0)
	s_barrier
	s_waitcnt lgkmcnt(0)
	v_mfma_f32_16x16x32_bf16 v[70:73], v[138:141], v[190:193], v[70:73]
	v_mfma_f32_16x16x32_bf16 v[66:69], v[146:149], v[190:193], v[66:69]
	v_mfma_f32_16x16x32_bf16 v[58:61], v[138:141], v[198:201], v[58:61]
	v_mfma_f32_16x16x32_bf16 v[50:53], v[146:149], v[198:201], v[50:53]
	v_mfma_f32_16x16x32_bf16 v[42:45], v[138:141], v[224:227], v[42:45]
	v_mfma_f32_16x16x32_bf16 v[34:37], v[146:149], v[224:227], v[34:37]
	v_mfma_f32_16x16x32_bf16 v[22:25], v[138:141], v[232:235], v[22:25]
	v_mfma_f32_16x16x32_bf16 v[18:21], v[146:149], v[232:235], v[18:21]
	v_mfma_f32_16x16x32_bf16 v[70:73], v[142:145], v[194:197], v[70:73]
	v_mfma_f32_16x16x32_bf16 v[66:69], v[150:153], v[194:197], v[66:69]
	v_mfma_f32_16x16x32_bf16 v[58:61], v[142:145], v[220:223], v[58:61]
	v_mfma_f32_16x16x32_bf16 v[50:53], v[150:153], v[220:223], v[50:53]
	v_mfma_f32_16x16x32_bf16 v[42:45], v[142:145], v[228:231], v[42:45]
	v_mfma_f32_16x16x32_bf16 v[34:37], v[150:153], v[228:231], v[34:37]
	v_mfma_f32_16x16x32_bf16 v[22:25], v[142:145], v[236:239], v[22:25]
	v_mfma_f32_16x16x32_bf16 v[18:21], v[150:153], v[236:239], v[18:21]
	v_mfma_f32_16x16x32_bf16 v[62:65], v[164:167], v[190:193], v[62:65]
	v_mfma_f32_16x16x32_bf16 v[54:57], v[182:185], v[190:193], v[54:57]
	v_mfma_f32_16x16x32_bf16 v[46:49], v[164:167], v[198:201], v[46:49]
	v_mfma_f32_16x16x32_bf16 v[38:41], v[182:185], v[198:201], v[38:41]
	v_mfma_f32_16x16x32_bf16 v[30:33], v[164:167], v[224:227], v[30:33]
	v_mfma_f32_16x16x32_bf16 v[26:29], v[182:185], v[224:227], v[26:29]
	v_mfma_f32_16x16x32_bf16 v[14:17], v[164:167], v[232:235], v[14:17]
	v_mfma_f32_16x16x32_bf16 v[10:13], v[182:185], v[232:235], v[10:13]
	v_mfma_f32_16x16x32_bf16 v[62:65], v[178:181], v[194:197], v[62:65]
	v_mfma_f32_16x16x32_bf16 v[54:57], v[186:189], v[194:197], v[54:57]
	v_mfma_f32_16x16x32_bf16 v[46:49], v[178:181], v[220:223], v[46:49]
	v_mfma_f32_16x16x32_bf16 v[38:41], v[186:189], v[220:223], v[38:41]
	v_mfma_f32_16x16x32_bf16 v[30:33], v[178:181], v[228:231], v[30:33]
	v_mfma_f32_16x16x32_bf16 v[26:29], v[186:189], v[228:231], v[26:29]
	v_mfma_f32_16x16x32_bf16 v[14:17], v[178:181], v[236:239], v[14:17]
	v_mfma_f32_16x16x32_bf16 v[10:13], v[186:189], v[236:239], v[10:13]
	s_barrier
	s_add_u32 s0, s0, 0x100
	s_addc_u32 s1, s1, 0
	s_add_u32 s3, s3, 0x100
	s_addc_u32 s10, s10, 0
	s_cmp_ge_u32 s26, s95
	s_mov_b32 s11, s26
	s_cbranch_scc1 .Lpeel_exit_328

; #define PG8_BAR __builtin_amdgcn_s_barrier()
; template <class Epi, bool ALIGN_EPI = true>
; __device__ __forceinline__ void gemm_phase(LAS unsigned char* lds, const Gemm g, const StaticOrder& S, const Epi& E) {
;     ...
;         if constexpr (ALIGN_EPI) { if (wr == 0) PG8_BAR; }
;         if constexpr (!Epi::AFTER_DRAIN) E.fast(acc, cur, wr, wc, fr, fq, rsc);
;         if (!has_next) break;
.Lpeel_exit_328:
	s_setprio 0
	s_and_b64 vcc, exec, s[18:19]
	s_cbranch_vccz .LBB0_331
	s_barrier
